# unrolled-by-4 loop: running bias scalars (2 fewer SALU, 1 fewer VALU per tile), staging address math placed in the M0 wait slots (2 fewer s_nop)
# speedup vs baseline: 1.0104x; 1.0025x over previous
; __device__ __forceinline__ void bias_init(f32x16& p0, f32x16& p1, float base, float nslope2, float nM2, int rel  ) {
;     if (rel <= -63 || rel >= 31) {
;         const float sg = (rel < 0) ? -nslope2 : nslope2, lbv = fmaf(-sg, base, nM2);
; #pragma unroll
;         for (int r = 0; r < 16; ++r) { p0[r] = fmaf((float)((r & 3) + 8 * (r >> 2)), sg, lbv); p1[r] = fmaf((float)((r & 3) + 8 * (r >> 2) + 32), sg, lbv); }
;     } else {
; #pragma unroll
;         for (int r = 0; r < 16; ++r) { const float d = base - (float)((r & 3) + 8 * (r >> 2));
;             p0[r] = fmaf(fabsf(d), nslope2, nM2); p1[r] = fmaf(fabsf(d - 32.f), nslope2, nM2); }
;     }
; }
; __device__ __forceinline__ void diff_unit(const DiffArgs& A, int b, int h, int qb, char* lds, int wv) {
;     ...
;     float l_reg = 0; f32x16 o[4] = {}; bf16x8 qr[4];
;     { const char* Qw = Pb + (size_t)(qb * 128 + wq * 32) * (INC * 2) + (C_DQ + c * 64) * 2; const unsigned qoff = (unsigned)((r32 * INC + hi * 8) * 2);
; #pragma unroll
;       for (int d0 = 0; d0 < 4; ++d0) qr[d0] = *reinterpret_cast<const bf16x8*>(Qw + qoff + d0 * 32); }
;     const int colB0 = c * 128;
;     const int krow = wid * 4 + (lane >> 4), kcc = (lane & 15) ^ (krow & 15);
;     const unsigned koff = (unsigned)((krow * INC + kcc * 8) * 2);
;     const int vkey = (wid >> 2) * 16 + (((wid >> 1) & 1) << 3) + (((lane >> 4) & 1) << 2) + ((lane >> 2) & 3)  , vcol = ((wid & 1) * 2 + (lane >> 5)) * 32 + (lane & 3) * 8;
;     const unsigned voff = (unsigned)((vkey * INC + vcol) * 2 + (C_DV - C_DK) * 2);
;     const int vb0 = (int)(uintptr_t)V_lds + v_rd_base(lane);
;     const char* Pk = Pb + (size_t)(t_lo * KVBLK) * (INC * 2) + C_DK * 2; int iposk = ipos - t_lo * KVBLK - 4 * hi; asm volatile("" : "+v"(iposk));     const int relw = t_lo * KVBLK - (qb * 128 + wq * 32);
;     typedef __attribute__((address_space(3))) unsigned lds_u32;
;     __attribute__((address_space(3))) unsigned char* ldsA = (__attribute__((address_space(3))) unsigned char*)lds + wid * 1024;
;     ...
;     f32x16 pA0, pA1, pB0, pB1; bf16x8 pa0, pa1, pa2, pa3; const int NT = nt;
;     STAGE(0); ENDI();
;     STAGE(1);
;     BIAS(pA0, pA1, 0); qkt<4>(pA0, pA1, K_lds, qr, r32, hi, colB0);
;     ...
;     if (c == 0) {
;     ...
;         const int lp_ = opaque_tid(wv) & 63, r32p = lp_ & 31, hip = lp_ >> 5;
;         exp_half(pA0);
;         ENDI();
; #pragma unroll 1
.Lsym_entry:
	v_mov_b32_e32 v0, 0
	v_mov_b32_e32 v1, 0
	v_mov_b32_e32 v2, 0
	v_mov_b32_e32 v3, 0
	v_mov_b32_e32 v4, 0
	v_mov_b32_e32 v5, 0
	v_mov_b32_e32 v6, 0
	v_mov_b32_e32 v7, 0
	v_mov_b32_e32 v8, 0
	v_mov_b32_e32 v9, 0
	v_mov_b32_e32 v10, 0
	v_mov_b32_e32 v11, 0
	v_mov_b32_e32 v12, 0
	v_mov_b32_e32 v13, 0
	v_mov_b32_e32 v14, 0
	v_mov_b32_e32 v15, 0
	v_mov_b32_e32 v16, 0
	v_mov_b32_e32 v17, 0
	v_mov_b32_e32 v18, 0
	v_mov_b32_e32 v19, 0
	v_mov_b32_e32 v20, 0
	v_mov_b32_e32 v21, 0
	v_mov_b32_e32 v22, 0
	v_mov_b32_e32 v23, 0
	v_mov_b32_e32 v24, 0
	v_mov_b32_e32 v25, 0
	v_mov_b32_e32 v26, 0
	v_mov_b32_e32 v27, 0
	v_mov_b32_e32 v28, 0
	v_mov_b32_e32 v29, 0
	v_mov_b32_e32 v30, 0
	v_mov_b32_e32 v31, 0
	v_mov_b32_e32 v32, 0
	v_mov_b32_e32 v33, 0
	v_mov_b32_e32 v34, 0
	v_mov_b32_e32 v35, 0
	v_mov_b32_e32 v36, 0
	v_mov_b32_e32 v37, 0
	v_mov_b32_e32 v38, 0
	v_mov_b32_e32 v39, 0
	v_mov_b32_e32 v40, 0
	v_mov_b32_e32 v41, 0
	v_mov_b32_e32 v42, 0
	v_mov_b32_e32 v43, 0
	v_mov_b32_e32 v44, 0
	v_mov_b32_e32 v45, 0
	v_mov_b32_e32 v46, 0
	v_mov_b32_e32 v47, 0
	v_mov_b32_e32 v48, 0
	v_mov_b32_e32 v49, 0
	v_mov_b32_e32 v50, 0
	v_mov_b32_e32 v51, 0
	v_mov_b32_e32 v52, 0
	v_mov_b32_e32 v53, 0
	v_mov_b32_e32 v54, 0
	v_mov_b32_e32 v55, 0
	v_mov_b32_e32 v56, 0
	v_mov_b32_e32 v57, 0
	v_mov_b32_e32 v58, 0
	v_mov_b32_e32 v59, 0
	v_mov_b32_e32 v60, 0
	v_mov_b32_e32 v61, 0
	v_mov_b32_e32 v62, 0
	v_mov_b32_e32 v63, 0
	v_mov_b32_e32 v182, 0
	v_mbcnt_lo_u32_b32 v190, -1, 0
	v_mbcnt_hi_u32_b32 v190, -1, v190
	v_and_b32_e32 v191, 31, v190
	v_lshrrev_b32_e32 v187, 5, v190
	v_lshlrev_b32_e32 v185, 4, v187
	v_or_b32_e32 v185, s52, v185
	v_and_b32_e32 v183, 15, v191
	v_lshlrev_b32_e32 v183, 4, v183
	v_xor_b32_e32 v185, v185, v183
	v_lshlrev_b32_e32 v183, 8, v191
	v_xor_b32_e32 v178, 0, v185
	v_add_u32_e32 v178, v178, v183
	v_add_u32_e32 v178, 0x10000, v178
	v_xor_b32_e32 v179, 32, v185
	v_add_u32_e32 v179, v179, v183
	v_add_u32_e32 v179, 0x10000, v179
	v_xor_b32_e32 v180, 64, v185
	v_add_u32_e32 v180, v180, v183
	v_add_u32_e32 v180, 0x10000, v180
	v_xor_b32_e32 v181, 96, v185
	v_add_u32_e32 v181, v181, v183
	v_add_u32_e32 v181, 0x10000, v181
	s_add_i32 s55, s63, 64
	v_subrev_u32_e32 v183, 64, v236
	v_cvt_f32_i32_e32 v183, v183
	s_mov_b32 s54, 0
	s_add_u32 s56, s20, 0x1c1e00
	s_addc_u32 s57, s21, 0
	v_exp_f32_e32 v80, v80
	v_exp_f32_e32 v81, v81
	v_exp_f32_e32 v82, v82
	v_exp_f32_e32 v83, v83
	v_add_f32_e32 v182, v80, v182
	v_add_f32_e32 v182, v81, v182
	v_cvt_pk_bf16_f32 v128, v80, v81
	v_exp_f32_e32 v84, v84
	v_exp_f32_e32 v85, v85
	v_add_f32_e32 v182, v82, v182
	v_add_f32_e32 v182, v83, v182
	v_cvt_pk_bf16_f32 v129, v82, v83
	v_exp_f32_e32 v86, v86
	v_exp_f32_e32 v87, v87
	v_add_f32_e32 v182, v84, v182
	v_add_f32_e32 v182, v85, v182
	v_cvt_pk_bf16_f32 v130, v84, v85
	v_add_f32_e32 v182, v86, v182
	v_add_f32_e32 v182, v87, v182
	v_cvt_pk_bf16_f32 v131, v86, v87
.Lsym_loop:
	s_waitcnt vmcnt(0)
	s_barrier
	ds_read_b128 v[192:195], v178 offset:16384
	ds_read_b128 v[196:199], v178 offset:24576
	ds_read_b128 v[200:203], v179 offset:16384
	ds_read_b128 v[204:207], v179 offset:24576
	ds_read_b128 v[208:211], v180 offset:16384
	ds_read_b128 v[212:215], v180 offset:24576
	ds_read_b128 v[216:219], v181 offset:16384
	ds_read_b128 v[220:223], v181 offset:24576
	s_add_i32 s53, s54, 2
	s_cmp_le_i32 s53, s62
	s_cbranch_scc0 .Lsym_nostage_s0
	s_add_i32 m0, s25, 0x8000
	s_add_u32 s60, s56, 0x70000
	s_addc_u32 s61, s57, 0
	global_load_lds_dwordx4 v176, s[56:57]
	s_add_i32 m0, s24, 0x8000
	s_nop 0
	global_load_lds_dwordx4 v188, s[56:57]
	s_add_i32 m0, s25, 0xa000
	s_add_u32 s56, s56, 0xe0000
	s_addc_u32 s57, s57, 0
	global_load_lds_dwordx4 v176, s[60:61]
	s_add_i32 m0, s24, 0xa000
	s_nop 0
	global_load_lds_dwordx4 v188, s[60:61]
.Lsym_nostage_s0:
	s_add_i32 s100, s55, 62
	s_cmp_lt_u32 s100, 93
	s_cbranch_scc1 .Lsym_diag_s0
	s_cmp_lt_i32 s55, 0
	s_cselect_b32 s100, -1.0, 1.0
	v_mul_f32_e32 v185, s100, v186
	v_fma_f32 v187, -v185, v183, s16
	v_fmamk_f32 v112, v185, 0x00000000, v187
	v_fmamk_f32 v96, v185, 0x42000000, v187
	v_fmamk_f32 v113, v185, 0x3f800000, v187
	v_fmamk_f32 v97, v185, 0x42040000, v187
	v_fmamk_f32 v114, v185, 0x40000000, v187
	v_fmamk_f32 v98, v185, 0x42080000, v187
	v_fmamk_f32 v115, v185, 0x40400000, v187
	v_fmamk_f32 v99, v185, 0x420c0000, v187
	v_fmamk_f32 v116, v185, 0x41000000, v187
	v_fmamk_f32 v100, v185, 0x42200000, v187
	v_fmamk_f32 v117, v185, 0x41100000, v187
	v_fmamk_f32 v101, v185, 0x42240000, v187
	v_fmamk_f32 v118, v185, 0x41200000, v187
	v_fmamk_f32 v102, v185, 0x42280000, v187
	v_fmamk_f32 v119, v185, 0x41300000, v187
	v_fmamk_f32 v103, v185, 0x422c0000, v187
	v_fmamk_f32 v120, v185, 0x41800000, v187
	v_fmamk_f32 v104, v185, 0x42400000, v187
	v_fmamk_f32 v121, v185, 0x41880000, v187
	v_fmamk_f32 v105, v185, 0x42440000, v187
	v_fmamk_f32 v122, v185, 0x41900000, v187
	v_fmamk_f32 v106, v185, 0x42480000, v187
	v_fmamk_f32 v123, v185, 0x41980000, v187
	v_fmamk_f32 v107, v185, 0x424c0000, v187
	v_fmamk_f32 v124, v185, 0x41c00000, v187
	v_fmamk_f32 v108, v185, 0x42600000, v187
	v_fmamk_f32 v125, v185, 0x41c80000, v187
	v_fmamk_f32 v109, v185, 0x42640000, v187
	v_fmamk_f32 v126, v185, 0x41d00000, v187
	v_fmamk_f32 v110, v185, 0x42680000, v187
	v_fmamk_f32 v127, v185, 0x41d80000, v187
	v_fmamk_f32 v111, v185, 0x426c0000, v187
	s_branch .Lsym_biasdone_s0

; template <int KS> __device__ __forceinline__ void pv_ks(f32x16* o, int vb, bf16x8 pa) {
;     const s16x4 l0 = tr_read<v_rd_off(0, KS, 0)>(vb), h0 = tr_read<v_rd_off(0, KS, 1)>(vb), l1 = tr_read<v_rd_off(1, KS, 0)>(vb), h1 = tr_read<v_rd_off(1, KS, 1)>(vb);
;     const s16x4 l2 = tr_read<v_rd_off(2, KS, 0)>(vb), h2 = tr_read<v_rd_off(2, KS, 1)>(vb), l3 = tr_read<v_rd_off(3, KS, 0)>(vb), h3 = tr_read<v_rd_off(3, KS, 1)>(vb);
;     ...
;     asm volatile("s_waitcnt lgkmcnt(6)" ::: "memory"); SBAR();
;     o[0] = __builtin_amdgcn_mfma_f32_32x32x16_bf16(pa, PK(l0, h0), o[0], 0, 0, 0);
;     asm volatile("s_waitcnt lgkmcnt(4)" ::: "memory"); SBAR();
;     o[1] = __builtin_amdgcn_mfma_f32_32x32x16_bf16(pa, PK(l1, h1), o[1], 0, 0, 0);
;     asm volatile("s_waitcnt lgkmcnt(2)" ::: "memory"); SBAR();
;     o[2] = __builtin_amdgcn_mfma_f32_32x32x16_bf16(pa, PK(l2, h2), o[2], 0, 0, 0);
;     asm volatile("s_waitcnt lgkmcnt(0)" ::: "memory"); SBAR();
;     o[3] = __builtin_amdgcn_mfma_f32_32x32x16_bf16(pa, PK(l3, h3), o[3], 0, 0, 0);
;     ...
; }
; __device__ __forceinline__ void pv_d0(f32x16* o, int vb, bf16x8 pa0, bf16x8 pa1, bf16x8 pa2, bf16x8 pa3) {
;     __builtin_amdgcn_s_setprio(1);
;     pv_ks<0>(o, vb, pa0); pv_ks<1>(o, vb, pa1); pv_ks<2>(o, vb, pa2); pv_ks<3>(o, vb, pa3);
;     __builtin_amdgcn_s_setprio(0);
; }
; __device__ __forceinline__ void exp_half(f32x16& p) {
; #pragma unroll
;     for (int r = 0; r < 16; ++r) p[r] = __builtin_amdgcn_exp2f(p[r]);
; }
; __device__ __forceinline__ void pack_p(const f32x16& p0, const f32x16& p1, float& l_reg, bf16x8& pa0, bf16x8& pa1, bf16x8& pa2, bf16x8& pa3) {
;     float ps = 0;
; #pragma unroll
;     for (int r = 0; r < 16; ++r) ps += p0[r];
; #pragma unroll
;     for (int r = 0; r < 16; ++r) ps += p1[r];
;     l_reg += ps;
;     ...
;     PK4(p0, 0, pa0); PK4(p0, 8, pa1); PK4(p1, 0, pa2); PK4(p1, 8, pa3);
;     ...
; }
; template <int ND0> __device__ __forceinline__ void qkt(f32x16& p0, f32x16& p1, const char* Ks, const bf16x8* qr, int r32, int hi, int colB0) {
; #pragma unroll
;     for (int d0 = 0; d0 < ND0; ++d0) { const int cb = colB0 + (d0 * 16 + hi * 8) * 2;
;         const bf16x8 b0 = *reinterpret_cast<const bf16x8*>(Ks + KSWZ(r32, cb));
;         const bf16x8 b1 = *reinterpret_cast<const bf16x8*>(Ks + KSWZ(32 + r32, cb));
;         p0 = __builtin_amdgcn_mfma_f32_32x32x16_bf16(b0, qr[d0], p0, 0, 0, 0);
.Lsym_biasdone_s0:
	s_add_i32 s55, s55, 64
	v_add_f32_e32 v183, 0xc2800000, v183
	ds_read_b64_tr_b16 v[144:145], v252 offset:0
	ds_read_b64_tr_b16 v[146:147], v252 offset:2048
	ds_read_b64_tr_b16 v[148:149], v252 offset:512
	ds_read_b64_tr_b16 v[150:151], v252 offset:2560
	ds_read_b64_tr_b16 v[152:153], v252 offset:1024
	ds_read_b64_tr_b16 v[154:155], v252 offset:3072
	ds_read_b64_tr_b16 v[156:157], v252 offset:1536
	ds_read_b64_tr_b16 v[158:159], v252 offset:3584
	s_waitcnt lgkmcnt(6)
	v_mfma_f32_32x32x16_bf16 v[48:63], v[128:131], v[144:147], v[48:63]
	ds_read_b64_tr_b16 v[144:145], v252 offset:4096
	ds_read_b64_tr_b16 v[146:147], v252 offset:6144
	v_exp_f32_e32 v88, v88
	v_exp_f32_e32 v89, v89
	s_waitcnt lgkmcnt(6)
	v_mfma_f32_32x32x16_bf16 v[32:47], v[128:131], v[148:151], v[32:47]
	ds_read_b64_tr_b16 v[148:149], v252 offset:4608
	ds_read_b64_tr_b16 v[150:151], v252 offset:6656
	v_exp_f32_e32 v90, v90
	v_exp_f32_e32 v91, v91
	v_add_f32_e32 v182, v88, v182
	v_add_f32_e32 v182, v89, v182
	v_cvt_pk_bf16_f32 v132, v88, v89
	s_waitcnt lgkmcnt(6)
	v_mfma_f32_32x32x16_bf16 v[16:31], v[128:131], v[152:155], v[16:31]
	ds_read_b64_tr_b16 v[152:153], v252 offset:5120
	ds_read_b64_tr_b16 v[154:155], v252 offset:7168
	v_exp_f32_e32 v92, v92
	v_exp_f32_e32 v93, v93
	v_add_f32_e32 v182, v90, v182
	v_add_f32_e32 v182, v91, v182
	v_cvt_pk_bf16_f32 v133, v90, v91
	s_waitcnt lgkmcnt(6)
	v_mfma_f32_32x32x16_bf16 v[0:15], v[128:131], v[156:159], v[0:15]
	ds_read_b64_tr_b16 v[156:157], v252 offset:5632
	ds_read_b64_tr_b16 v[158:159], v252 offset:7680
	v_exp_f32_e32 v94, v94
	v_exp_f32_e32 v95, v95
	v_add_f32_e32 v182, v92, v182
	v_add_f32_e32 v182, v93, v182
	v_cvt_pk_bf16_f32 v134, v92, v93
	v_add_f32_e32 v182, v94, v182
	v_add_f32_e32 v182, v95, v182
	v_cvt_pk_bf16_f32 v135, v94, v95
	v_mfma_f32_32x32x16_bf16 v[112:127], v[192:195], v[172:175], v[112:127]
	v_mfma_f32_32x32x16_bf16 v[96:111], v[196:199], v[172:175], v[96:111]
	v_mfma_f32_32x32x16_bf16 v[112:127], v[200:203], v[168:171], v[112:127]
	v_mfma_f32_32x32x16_bf16 v[96:111], v[204:207], v[168:171], v[96:111]
	s_waitcnt lgkmcnt(6)
	v_mfma_f32_32x32x16_bf16 v[48:63], v[132:135], v[144:147], v[48:63]
	ds_read_b64_tr_b16 v[144:145], v252 offset:8192
	ds_read_b64_tr_b16 v[146:147], v252 offset:10240
	v_exp_f32_e32 v64, v64
	v_exp_f32_e32 v65, v65
	s_waitcnt lgkmcnt(6)
	v_mfma_f32_32x32x16_bf16 v[32:47], v[132:135], v[148:151], v[32:47]
	ds_read_b64_tr_b16 v[148:149], v252 offset:8704
	ds_read_b64_tr_b16 v[150:151], v252 offset:10752
	v_exp_f32_e32 v66, v66
	v_exp_f32_e32 v67, v67
	v_add_f32_e32 v182, v64, v182
	v_add_f32_e32 v182, v65, v182
	v_cvt_pk_bf16_f32 v136, v64, v65
	s_waitcnt lgkmcnt(6)
	v_mfma_f32_32x32x16_bf16 v[16:31], v[132:135], v[152:155], v[16:31]
	ds_read_b64_tr_b16 v[152:153], v252 offset:9216
	ds_read_b64_tr_b16 v[154:155], v252 offset:11264
	v_exp_f32_e32 v68, v68
	v_exp_f32_e32 v69, v69
	v_add_f32_e32 v182, v66, v182
	v_add_f32_e32 v182, v67, v182
	v_cvt_pk_bf16_f32 v137, v66, v67
	s_waitcnt lgkmcnt(6)
	v_mfma_f32_32x32x16_bf16 v[0:15], v[132:135], v[156:159], v[0:15]
	ds_read_b64_tr_b16 v[156:157], v252 offset:9728
	ds_read_b64_tr_b16 v[158:159], v252 offset:11776
	v_exp_f32_e32 v70, v70
	v_exp_f32_e32 v71, v71
	v_add_f32_e32 v182, v68, v182
	v_add_f32_e32 v182, v69, v182
	v_cvt_pk_bf16_f32 v138, v68, v69
	v_add_f32_e32 v182, v70, v182
	v_add_f32_e32 v182, v71, v182
	v_cvt_pk_bf16_f32 v139, v70, v71
	v_mfma_f32_32x32x16_bf16 v[112:127], v[208:211], v[164:167], v[112:127]
	v_mfma_f32_32x32x16_bf16 v[96:111], v[212:215], v[164:167], v[96:111]
	v_mfma_f32_32x32x16_bf16 v[112:127], v[216:219], v[160:163], v[112:127]
	v_mfma_f32_32x32x16_bf16 v[96:111], v[220:223], v[160:163], v[96:111]
	s_waitcnt lgkmcnt(6)
	v_mfma_f32_32x32x16_bf16 v[48:63], v[136:139], v[144:147], v[48:63]
	ds_read_b64_tr_b16 v[144:145], v252 offset:12288
	ds_read_b64_tr_b16 v[146:147], v252 offset:14336
	v_exp_f32_e32 v72, v72
	v_exp_f32_e32 v73, v73
	s_waitcnt lgkmcnt(6)
	v_mfma_f32_32x32x16_bf16 v[32:47], v[136:139], v[148:151], v[32:47]
	ds_read_b64_tr_b16 v[148:149], v252 offset:12800
	ds_read_b64_tr_b16 v[150:151], v252 offset:14848
	v_exp_f32_e32 v74, v74
	v_exp_f32_e32 v75, v75
	v_add_f32_e32 v182, v72, v182
	v_add_f32_e32 v182, v73, v182
	v_cvt_pk_bf16_f32 v140, v72, v73
	s_waitcnt lgkmcnt(6)
	v_mfma_f32_32x32x16_bf16 v[16:31], v[136:139], v[152:155], v[16:31]
	ds_read_b64_tr_b16 v[152:153], v252 offset:13312
	ds_read_b64_tr_b16 v[154:155], v252 offset:15360
	v_exp_f32_e32 v76, v76
	v_exp_f32_e32 v77, v77
	v_add_f32_e32 v182, v74, v182
	v_add_f32_e32 v182, v75, v182
	v_cvt_pk_bf16_f32 v141, v74, v75
	s_waitcnt lgkmcnt(6)
	v_mfma_f32_32x32x16_bf16 v[0:15], v[136:139], v[156:159], v[0:15]
	ds_read_b64_tr_b16 v[156:157], v252 offset:13824
	ds_read_b64_tr_b16 v[158:159], v252 offset:15872
	v_exp_f32_e32 v78, v78
	v_exp_f32_e32 v79, v79
	v_add_f32_e32 v182, v76, v182
	v_add_f32_e32 v182, v77, v182
	v_cvt_pk_bf16_f32 v142, v76, v77
	v_add_f32_e32 v182, v78, v182
	v_add_f32_e32 v182, v79, v182
	v_cvt_pk_bf16_f32 v143, v78, v79
	s_nop 1
	s_waitcnt lgkmcnt(6)
	v_mfma_f32_32x32x16_bf16 v[48:63], v[140:143], v[144:147], v[48:63]
	v_exp_f32_e32 v112, v112
	v_exp_f32_e32 v113, v113
	s_waitcnt lgkmcnt(4)
	v_mfma_f32_32x32x16_bf16 v[32:47], v[140:143], v[148:151], v[32:47]
	v_exp_f32_e32 v114, v114
	v_exp_f32_e32 v115, v115
	v_add_f32_e32 v182, v112, v182
	v_add_f32_e32 v182, v113, v182
	v_cvt_pk_bf16_f32 v128, v112, v113
	s_waitcnt lgkmcnt(2)
	v_mfma_f32_32x32x16_bf16 v[16:31], v[140:143], v[152:155], v[16:31]
	v_exp_f32_e32 v116, v116
	v_exp_f32_e32 v117, v117
	v_add_f32_e32 v182, v114, v182
	v_add_f32_e32 v182, v115, v182
	v_cvt_pk_bf16_f32 v129, v114, v115
	s_waitcnt lgkmcnt(0)
	v_mfma_f32_32x32x16_bf16 v[0:15], v[140:143], v[156:159], v[0:15]
	v_exp_f32_e32 v118, v118
	v_exp_f32_e32 v119, v119
	v_add_f32_e32 v182, v116, v182
	v_add_f32_e32 v182, v117, v182
	v_cvt_pk_bf16_f32 v130, v116, v117
	v_add_f32_e32 v182, v118, v182
	v_add_f32_e32 v182, v119, v182
	v_cvt_pk_bf16_f32 v131, v118, v119
	s_nop 1
	s_add_i32 s54, s54, 1
	s_cmp_ge_i32 s54, s62
	s_cbranch_scc1 .Lsym_last1
	s_waitcnt vmcnt(0)
	s_barrier
	ds_read_b128 v[192:195], v178 offset:32768
	ds_read_b128 v[196:199], v178 offset:40960
	ds_read_b128 v[200:203], v179 offset:32768
	ds_read_b128 v[204:207], v179 offset:40960
	ds_read_b128 v[208:211], v180 offset:32768
	ds_read_b128 v[212:215], v180 offset:40960
	ds_read_b128 v[216:219], v181 offset:32768
	ds_read_b128 v[220:223], v181 offset:40960
	s_add_i32 s53, s54, 2
	s_cmp_le_i32 s53, s62
	s_cbranch_scc0 .Lsym_nostage_s1
	s_add_i32 m0, s25, 0xc000
	s_add_u32 s60, s56, 0x70000
	s_addc_u32 s61, s57, 0
	global_load_lds_dwordx4 v176, s[56:57]
	s_add_i32 m0, s24, 0xc000
	s_nop 0
	global_load_lds_dwordx4 v188, s[56:57]
	s_add_i32 m0, s25, 0xe000
	s_add_u32 s56, s56, 0xe0000
	s_addc_u32 s57, s57, 0
	global_load_lds_dwordx4 v176, s[60:61]
	s_add_i32 m0, s24, 0xe000
	s_nop 0
	global_load_lds_dwordx4 v188, s[60:61]
; __device__ __forceinline__ void bias_init(f32x16& p0, f32x16& p1, float base, float nslope2, float nM2, int rel  ) {
;     if (rel <= -63 || rel >= 31) {
;         const float sg = (rel < 0) ? -nslope2 : nslope2, lbv = fmaf(-sg, base, nM2);
; #pragma unroll
;         for (int r = 0; r < 16; ++r) { p0[r] = fmaf((float)((r & 3) + 8 * (r >> 2)), sg, lbv); p1[r] = fmaf((float)((r & 3) + 8 * (r >> 2) + 32), sg, lbv); }
;     } else {
; #pragma unroll
;         for (int r = 0; r < 16; ++r) { const float d = base - (float)((r & 3) + 8 * (r >> 2));
;             p0[r] = fmaf(fabsf(d), nslope2, nM2); p1[r] = fmaf(fabsf(d - 32.f), nslope2, nM2); }
;     }
; }
.Lsym_nostage_s1:
	s_add_i32 s100, s55, 62
	s_cmp_lt_u32 s100, 93
	s_cbranch_scc1 .Lsym_diag_s1
	s_cmp_lt_i32 s55, 0
	s_cselect_b32 s100, -1.0, 1.0
	v_mul_f32_e32 v185, s100, v186
	v_fma_f32 v187, -v185, v183, s16
	v_fmamk_f32 v80, v185, 0x00000000, v187
	v_fmamk_f32 v64, v185, 0x42000000, v187
	v_fmamk_f32 v81, v185, 0x3f800000, v187
	v_fmamk_f32 v65, v185, 0x42040000, v187
	v_fmamk_f32 v82, v185, 0x40000000, v187
	v_fmamk_f32 v66, v185, 0x42080000, v187
	v_fmamk_f32 v83, v185, 0x40400000, v187
	v_fmamk_f32 v67, v185, 0x420c0000, v187
	v_fmamk_f32 v84, v185, 0x41000000, v187
	v_fmamk_f32 v68, v185, 0x42200000, v187
	v_fmamk_f32 v85, v185, 0x41100000, v187
	v_fmamk_f32 v69, v185, 0x42240000, v187
	v_fmamk_f32 v86, v185, 0x41200000, v187
	v_fmamk_f32 v70, v185, 0x42280000, v187
	v_fmamk_f32 v87, v185, 0x41300000, v187
	v_fmamk_f32 v71, v185, 0x422c0000, v187
	v_fmamk_f32 v88, v185, 0x41800000, v187
	v_fmamk_f32 v72, v185, 0x42400000, v187
	v_fmamk_f32 v89, v185, 0x41880000, v187
	v_fmamk_f32 v73, v185, 0x42440000, v187
	v_fmamk_f32 v90, v185, 0x41900000, v187
	v_fmamk_f32 v74, v185, 0x42480000, v187
	v_fmamk_f32 v91, v185, 0x41980000, v187
	v_fmamk_f32 v75, v185, 0x424c0000, v187
	v_fmamk_f32 v92, v185, 0x41c00000, v187
	v_fmamk_f32 v76, v185, 0x42600000, v187
	v_fmamk_f32 v93, v185, 0x41c80000, v187
	v_fmamk_f32 v77, v185, 0x42640000, v187
	v_fmamk_f32 v94, v185, 0x41d00000, v187
	v_fmamk_f32 v78, v185, 0x42680000, v187
	v_fmamk_f32 v95, v185, 0x41d80000, v187
	v_fmamk_f32 v79, v185, 0x426c0000, v187
	s_branch .Lsym_biasdone_s1

; template <int KS> __device__ __forceinline__ void pv_ks(f32x16* o, int vb, bf16x8 pa) {
;     const s16x4 l0 = tr_read<v_rd_off(0, KS, 0)>(vb), h0 = tr_read<v_rd_off(0, KS, 1)>(vb), l1 = tr_read<v_rd_off(1, KS, 0)>(vb), h1 = tr_read<v_rd_off(1, KS, 1)>(vb);
;     const s16x4 l2 = tr_read<v_rd_off(2, KS, 0)>(vb), h2 = tr_read<v_rd_off(2, KS, 1)>(vb), l3 = tr_read<v_rd_off(3, KS, 0)>(vb), h3 = tr_read<v_rd_off(3, KS, 1)>(vb);
;     ...
;     asm volatile("s_waitcnt lgkmcnt(6)" ::: "memory"); SBAR();
;     o[0] = __builtin_amdgcn_mfma_f32_32x32x16_bf16(pa, PK(l0, h0), o[0], 0, 0, 0);
;     asm volatile("s_waitcnt lgkmcnt(4)" ::: "memory"); SBAR();
;     o[1] = __builtin_amdgcn_mfma_f32_32x32x16_bf16(pa, PK(l1, h1), o[1], 0, 0, 0);
;     asm volatile("s_waitcnt lgkmcnt(2)" ::: "memory"); SBAR();
;     o[2] = __builtin_amdgcn_mfma_f32_32x32x16_bf16(pa, PK(l2, h2), o[2], 0, 0, 0);
;     asm volatile("s_waitcnt lgkmcnt(0)" ::: "memory"); SBAR();
;     o[3] = __builtin_amdgcn_mfma_f32_32x32x16_bf16(pa, PK(l3, h3), o[3], 0, 0, 0);
;     ...
; }
; __device__ __forceinline__ void pv_d0(f32x16* o, int vb, bf16x8 pa0, bf16x8 pa1, bf16x8 pa2, bf16x8 pa3) {
;     __builtin_amdgcn_s_setprio(1);
;     pv_ks<0>(o, vb, pa0); pv_ks<1>(o, vb, pa1); pv_ks<2>(o, vb, pa2); pv_ks<3>(o, vb, pa3);
;     __builtin_amdgcn_s_setprio(0);
; }
; __device__ __forceinline__ void exp_half(f32x16& p) {
; #pragma unroll
;     for (int r = 0; r < 16; ++r) p[r] = __builtin_amdgcn_exp2f(p[r]);
; }
; __device__ __forceinline__ void pack_p(const f32x16& p0, const f32x16& p1, float& l_reg, bf16x8& pa0, bf16x8& pa1, bf16x8& pa2, bf16x8& pa3) {
;     float ps = 0;
; #pragma unroll
;     for (int r = 0; r < 16; ++r) ps += p0[r];
; #pragma unroll
;     for (int r = 0; r < 16; ++r) ps += p1[r];
;     l_reg += ps;
;     ...
;     PK4(p0, 0, pa0); PK4(p0, 8, pa1); PK4(p1, 0, pa2); PK4(p1, 8, pa3);
;     ...
; }
; template <int ND0> __device__ __forceinline__ void qkt(f32x16& p0, f32x16& p1, const char* Ks, const bf16x8* qr, int r32, int hi, int colB0) {
; #pragma unroll
;     for (int d0 = 0; d0 < ND0; ++d0) { const int cb = colB0 + (d0 * 16 + hi * 8) * 2;
;         const bf16x8 b0 = *reinterpret_cast<const bf16x8*>(Ks + KSWZ(r32, cb));
;         const bf16x8 b1 = *reinterpret_cast<const bf16x8*>(Ks + KSWZ(32 + r32, cb));
;         p0 = __builtin_amdgcn_mfma_f32_32x32x16_bf16(b0, qr[d0], p0, 0, 0, 0);
.Lsym_biasdone_s1:
	s_add_i32 s55, s55, 64
	v_add_f32_e32 v183, 0xc2800000, v183
	ds_read_b64_tr_b16 v[144:145], v252 offset:16384
	ds_read_b64_tr_b16 v[146:147], v252 offset:18432
	ds_read_b64_tr_b16 v[148:149], v252 offset:16896
	ds_read_b64_tr_b16 v[150:151], v252 offset:18944
	ds_read_b64_tr_b16 v[152:153], v252 offset:17408
	ds_read_b64_tr_b16 v[154:155], v252 offset:19456
	ds_read_b64_tr_b16 v[156:157], v252 offset:17920
	ds_read_b64_tr_b16 v[158:159], v252 offset:19968
	s_waitcnt lgkmcnt(6)
	v_mfma_f32_32x32x16_bf16 v[48:63], v[128:131], v[144:147], v[48:63]
	ds_read_b64_tr_b16 v[144:145], v252 offset:20480
	ds_read_b64_tr_b16 v[146:147], v252 offset:22528
	v_exp_f32_e32 v120, v120
	v_exp_f32_e32 v121, v121
	s_waitcnt lgkmcnt(6)
	v_mfma_f32_32x32x16_bf16 v[32:47], v[128:131], v[148:151], v[32:47]
	ds_read_b64_tr_b16 v[148:149], v252 offset:20992
	ds_read_b64_tr_b16 v[150:151], v252 offset:23040
	v_exp_f32_e32 v122, v122
	v_exp_f32_e32 v123, v123
	v_add_f32_e32 v182, v120, v182
	v_add_f32_e32 v182, v121, v182
	v_cvt_pk_bf16_f32 v132, v120, v121
	s_waitcnt lgkmcnt(6)
	v_mfma_f32_32x32x16_bf16 v[16:31], v[128:131], v[152:155], v[16:31]
	ds_read_b64_tr_b16 v[152:153], v252 offset:21504
	ds_read_b64_tr_b16 v[154:155], v252 offset:23552
	v_exp_f32_e32 v124, v124
	v_exp_f32_e32 v125, v125
	v_add_f32_e32 v182, v122, v182
	v_add_f32_e32 v182, v123, v182
	v_cvt_pk_bf16_f32 v133, v122, v123
	s_waitcnt lgkmcnt(6)
	v_mfma_f32_32x32x16_bf16 v[0:15], v[128:131], v[156:159], v[0:15]
	ds_read_b64_tr_b16 v[156:157], v252 offset:22016
	ds_read_b64_tr_b16 v[158:159], v252 offset:24064
	v_exp_f32_e32 v126, v126
	v_exp_f32_e32 v127, v127
	v_add_f32_e32 v182, v124, v182
	v_add_f32_e32 v182, v125, v182
	v_cvt_pk_bf16_f32 v134, v124, v125
	v_add_f32_e32 v182, v126, v182
	v_add_f32_e32 v182, v127, v182
	v_cvt_pk_bf16_f32 v135, v126, v127
	v_mfma_f32_32x32x16_bf16 v[80:95], v[192:195], v[172:175], v[80:95]
	v_mfma_f32_32x32x16_bf16 v[64:79], v[196:199], v[172:175], v[64:79]
	v_mfma_f32_32x32x16_bf16 v[80:95], v[200:203], v[168:171], v[80:95]
	v_mfma_f32_32x32x16_bf16 v[64:79], v[204:207], v[168:171], v[64:79]
	s_waitcnt lgkmcnt(6)
	v_mfma_f32_32x32x16_bf16 v[48:63], v[132:135], v[144:147], v[48:63]
	ds_read_b64_tr_b16 v[144:145], v252 offset:24576
	ds_read_b64_tr_b16 v[146:147], v252 offset:26624
	v_exp_f32_e32 v96, v96
	v_exp_f32_e32 v97, v97
	s_waitcnt lgkmcnt(6)
	v_mfma_f32_32x32x16_bf16 v[32:47], v[132:135], v[148:151], v[32:47]
	ds_read_b64_tr_b16 v[148:149], v252 offset:25088
	ds_read_b64_tr_b16 v[150:151], v252 offset:27136
	v_exp_f32_e32 v98, v98
	v_exp_f32_e32 v99, v99
	v_add_f32_e32 v182, v96, v182
	v_add_f32_e32 v182, v97, v182
	v_cvt_pk_bf16_f32 v136, v96, v97
	s_waitcnt lgkmcnt(6)
	v_mfma_f32_32x32x16_bf16 v[16:31], v[132:135], v[152:155], v[16:31]
	ds_read_b64_tr_b16 v[152:153], v252 offset:25600
	ds_read_b64_tr_b16 v[154:155], v252 offset:27648
	v_exp_f32_e32 v100, v100
	v_exp_f32_e32 v101, v101
	v_add_f32_e32 v182, v98, v182
	v_add_f32_e32 v182, v99, v182
	v_cvt_pk_bf16_f32 v137, v98, v99
	s_waitcnt lgkmcnt(6)
	v_mfma_f32_32x32x16_bf16 v[0:15], v[132:135], v[156:159], v[0:15]
	ds_read_b64_tr_b16 v[156:157], v252 offset:26112
	ds_read_b64_tr_b16 v[158:159], v252 offset:28160
	v_exp_f32_e32 v102, v102
	v_exp_f32_e32 v103, v103
	v_add_f32_e32 v182, v100, v182
	v_add_f32_e32 v182, v101, v182
	v_cvt_pk_bf16_f32 v138, v100, v101
	v_add_f32_e32 v182, v102, v182
	v_add_f32_e32 v182, v103, v182
	v_cvt_pk_bf16_f32 v139, v102, v103
	v_mfma_f32_32x32x16_bf16 v[80:95], v[208:211], v[164:167], v[80:95]
	v_mfma_f32_32x32x16_bf16 v[64:79], v[212:215], v[164:167], v[64:79]
	v_mfma_f32_32x32x16_bf16 v[80:95], v[216:219], v[160:163], v[80:95]
	v_mfma_f32_32x32x16_bf16 v[64:79], v[220:223], v[160:163], v[64:79]
	s_waitcnt lgkmcnt(6)
	v_mfma_f32_32x32x16_bf16 v[48:63], v[136:139], v[144:147], v[48:63]
	ds_read_b64_tr_b16 v[144:145], v252 offset:28672
	ds_read_b64_tr_b16 v[146:147], v252 offset:30720
	v_exp_f32_e32 v104, v104
	v_exp_f32_e32 v105, v105
	s_waitcnt lgkmcnt(6)
	v_mfma_f32_32x32x16_bf16 v[32:47], v[136:139], v[148:151], v[32:47]
	ds_read_b64_tr_b16 v[148:149], v252 offset:29184
	ds_read_b64_tr_b16 v[150:151], v252 offset:31232
	v_exp_f32_e32 v106, v106
	v_exp_f32_e32 v107, v107
	v_add_f32_e32 v182, v104, v182
	v_add_f32_e32 v182, v105, v182
	v_cvt_pk_bf16_f32 v140, v104, v105
	s_waitcnt lgkmcnt(6)
	v_mfma_f32_32x32x16_bf16 v[16:31], v[136:139], v[152:155], v[16:31]
	ds_read_b64_tr_b16 v[152:153], v252 offset:29696
	ds_read_b64_tr_b16 v[154:155], v252 offset:31744
	v_exp_f32_e32 v108, v108
	v_exp_f32_e32 v109, v109
	v_add_f32_e32 v182, v106, v182
	v_add_f32_e32 v182, v107, v182
	v_cvt_pk_bf16_f32 v141, v106, v107
	s_waitcnt lgkmcnt(6)
	v_mfma_f32_32x32x16_bf16 v[0:15], v[136:139], v[156:159], v[0:15]
	ds_read_b64_tr_b16 v[156:157], v252 offset:30208
	ds_read_b64_tr_b16 v[158:159], v252 offset:32256
	v_exp_f32_e32 v110, v110
	v_exp_f32_e32 v111, v111
	v_add_f32_e32 v182, v108, v182
	v_add_f32_e32 v182, v109, v182
	v_cvt_pk_bf16_f32 v142, v108, v109
	v_add_f32_e32 v182, v110, v182
	v_add_f32_e32 v182, v111, v182
	v_cvt_pk_bf16_f32 v143, v110, v111
	s_nop 1
	s_waitcnt lgkmcnt(6)
	v_mfma_f32_32x32x16_bf16 v[48:63], v[140:143], v[144:147], v[48:63]
	v_exp_f32_e32 v80, v80
	v_exp_f32_e32 v81, v81
	s_waitcnt lgkmcnt(4)
	v_mfma_f32_32x32x16_bf16 v[32:47], v[140:143], v[148:151], v[32:47]
	v_exp_f32_e32 v82, v82
	v_exp_f32_e32 v83, v83
	v_add_f32_e32 v182, v80, v182
	v_add_f32_e32 v182, v81, v182
	v_cvt_pk_bf16_f32 v128, v80, v81
	s_waitcnt lgkmcnt(2)
	v_mfma_f32_32x32x16_bf16 v[16:31], v[140:143], v[152:155], v[16:31]
	v_exp_f32_e32 v84, v84
	v_exp_f32_e32 v85, v85
	v_add_f32_e32 v182, v82, v182
	v_add_f32_e32 v182, v83, v182
	v_cvt_pk_bf16_f32 v129, v82, v83
	s_waitcnt lgkmcnt(0)
	v_mfma_f32_32x32x16_bf16 v[0:15], v[140:143], v[156:159], v[0:15]
	v_exp_f32_e32 v86, v86
	v_exp_f32_e32 v87, v87
	v_add_f32_e32 v182, v84, v182
	v_add_f32_e32 v182, v85, v182
	v_cvt_pk_bf16_f32 v130, v84, v85
	v_add_f32_e32 v182, v86, v182
	v_add_f32_e32 v182, v87, v182
	v_cvt_pk_bf16_f32 v131, v86, v87
	s_nop 1
	s_add_i32 s54, s54, 1
	s_waitcnt vmcnt(0)
	s_barrier
	ds_read_b128 v[192:195], v178 offset:49152
	ds_read_b128 v[196:199], v178 offset:57344
	ds_read_b128 v[200:203], v179 offset:49152
	ds_read_b128 v[204:207], v179 offset:57344
	ds_read_b128 v[208:211], v180 offset:49152
	ds_read_b128 v[212:215], v180 offset:57344
	ds_read_b128 v[216:219], v181 offset:49152
	ds_read_b128 v[220:223], v181 offset:57344
	s_add_i32 s53, s54, 2
	s_cmp_le_i32 s53, s62
	s_cbranch_scc0 .Lsym_nostage_s2
	s_add_i32 m0, s25, 0x0
	s_add_u32 s60, s56, 0x70000
	s_addc_u32 s61, s57, 0
	global_load_lds_dwordx4 v176, s[56:57]
	s_add_i32 m0, s24, 0x0
	s_nop 0
	global_load_lds_dwordx4 v188, s[56:57]
	s_add_i32 m0, s25, 0x2000
	s_add_u32 s56, s56, 0xe0000
	s_addc_u32 s57, s57, 0
	global_load_lds_dwordx4 v176, s[60:61]
	s_add_i32 m0, s24, 0x2000
	s_nop 0
	global_load_lds_dwordx4 v188, s[60:61]

; template <int KS> __device__ __forceinline__ void pv_ks(f32x16* o, int vb, bf16x8 pa) {
;     const s16x4 l0 = tr_read<v_rd_off(0, KS, 0)>(vb), h0 = tr_read<v_rd_off(0, KS, 1)>(vb), l1 = tr_read<v_rd_off(1, KS, 0)>(vb), h1 = tr_read<v_rd_off(1, KS, 1)>(vb);
;     const s16x4 l2 = tr_read<v_rd_off(2, KS, 0)>(vb), h2 = tr_read<v_rd_off(2, KS, 1)>(vb), l3 = tr_read<v_rd_off(3, KS, 0)>(vb), h3 = tr_read<v_rd_off(3, KS, 1)>(vb);
;     ...
;     asm volatile("s_waitcnt lgkmcnt(6)" ::: "memory"); SBAR();
;     o[0] = __builtin_amdgcn_mfma_f32_32x32x16_bf16(pa, PK(l0, h0), o[0], 0, 0, 0);
;     asm volatile("s_waitcnt lgkmcnt(4)" ::: "memory"); SBAR();
;     o[1] = __builtin_amdgcn_mfma_f32_32x32x16_bf16(pa, PK(l1, h1), o[1], 0, 0, 0);
;     asm volatile("s_waitcnt lgkmcnt(2)" ::: "memory"); SBAR();
;     o[2] = __builtin_amdgcn_mfma_f32_32x32x16_bf16(pa, PK(l2, h2), o[2], 0, 0, 0);
;     asm volatile("s_waitcnt lgkmcnt(0)" ::: "memory"); SBAR();
;     o[3] = __builtin_amdgcn_mfma_f32_32x32x16_bf16(pa, PK(l3, h3), o[3], 0, 0, 0);
;     ...
; }
; __device__ __forceinline__ void pv_d0(f32x16* o, int vb, bf16x8 pa0, bf16x8 pa1, bf16x8 pa2, bf16x8 pa3) {
;     __builtin_amdgcn_s_setprio(1);
;     pv_ks<0>(o, vb, pa0); pv_ks<1>(o, vb, pa1); pv_ks<2>(o, vb, pa2); pv_ks<3>(o, vb, pa3);
;     __builtin_amdgcn_s_setprio(0);
; }
; __device__ __forceinline__ void exp_half(f32x16& p) {
; #pragma unroll
;     for (int r = 0; r < 16; ++r) p[r] = __builtin_amdgcn_exp2f(p[r]);
; }
; __device__ __forceinline__ void pack_p(const f32x16& p0, const f32x16& p1, float& l_reg, bf16x8& pa0, bf16x8& pa1, bf16x8& pa2, bf16x8& pa3) {
;     float ps = 0;
; #pragma unroll
;     for (int r = 0; r < 16; ++r) ps += p0[r];
; #pragma unroll
;     for (int r = 0; r < 16; ++r) ps += p1[r];
;     l_reg += ps;
;     ...
;     PK4(p0, 0, pa0); PK4(p0, 8, pa1); PK4(p1, 0, pa2); PK4(p1, 8, pa3);
;     ...
; }
; template <int ND0> __device__ __forceinline__ void qkt(f32x16& p0, f32x16& p1, const char* Ks, const bf16x8* qr, int r32, int hi, int colB0) {
; #pragma unroll
;     for (int d0 = 0; d0 < ND0; ++d0) { const int cb = colB0 + (d0 * 16 + hi * 8) * 2;
;         const bf16x8 b0 = *reinterpret_cast<const bf16x8*>(Ks + KSWZ(r32, cb));
;         const bf16x8 b1 = *reinterpret_cast<const bf16x8*>(Ks + KSWZ(32 + r32, cb));
;         p0 = __builtin_amdgcn_mfma_f32_32x32x16_bf16(b0, qr[d0], p0, 0, 0, 0);
.Lsym_biasdone_s2:
	s_add_i32 s55, s55, 64
	v_add_f32_e32 v183, 0xc2800000, v183
	ds_read_b64_tr_b16 v[144:145], v252 offset:32768
	ds_read_b64_tr_b16 v[146:147], v252 offset:34816
	ds_read_b64_tr_b16 v[148:149], v252 offset:33280
	ds_read_b64_tr_b16 v[150:151], v252 offset:35328
	ds_read_b64_tr_b16 v[152:153], v252 offset:33792
	ds_read_b64_tr_b16 v[154:155], v252 offset:35840
	ds_read_b64_tr_b16 v[156:157], v252 offset:34304
	ds_read_b64_tr_b16 v[158:159], v252 offset:36352
	s_waitcnt lgkmcnt(6)
	v_mfma_f32_32x32x16_bf16 v[48:63], v[128:131], v[144:147], v[48:63]
	ds_read_b64_tr_b16 v[144:145], v252 offset:36864
	ds_read_b64_tr_b16 v[146:147], v252 offset:38912
	v_exp_f32_e32 v88, v88
	v_exp_f32_e32 v89, v89
	s_waitcnt lgkmcnt(6)
	v_mfma_f32_32x32x16_bf16 v[32:47], v[128:131], v[148:151], v[32:47]
	ds_read_b64_tr_b16 v[148:149], v252 offset:37376
	ds_read_b64_tr_b16 v[150:151], v252 offset:39424
	v_exp_f32_e32 v90, v90
	v_exp_f32_e32 v91, v91
	v_add_f32_e32 v182, v88, v182
	v_add_f32_e32 v182, v89, v182
	v_cvt_pk_bf16_f32 v132, v88, v89
	s_waitcnt lgkmcnt(6)
	v_mfma_f32_32x32x16_bf16 v[16:31], v[128:131], v[152:155], v[16:31]
	ds_read_b64_tr_b16 v[152:153], v252 offset:37888
	ds_read_b64_tr_b16 v[154:155], v252 offset:39936
	v_exp_f32_e32 v92, v92
	v_exp_f32_e32 v93, v93
	v_add_f32_e32 v182, v90, v182
	v_add_f32_e32 v182, v91, v182
	v_cvt_pk_bf16_f32 v133, v90, v91
	s_waitcnt lgkmcnt(6)
	v_mfma_f32_32x32x16_bf16 v[0:15], v[128:131], v[156:159], v[0:15]
	ds_read_b64_tr_b16 v[156:157], v252 offset:38400
	ds_read_b64_tr_b16 v[158:159], v252 offset:40448
	v_exp_f32_e32 v94, v94
	v_exp_f32_e32 v95, v95
	v_add_f32_e32 v182, v92, v182
	v_add_f32_e32 v182, v93, v182
	v_cvt_pk_bf16_f32 v134, v92, v93
	v_add_f32_e32 v182, v94, v182
	v_add_f32_e32 v182, v95, v182
	v_cvt_pk_bf16_f32 v135, v94, v95
	v_mfma_f32_32x32x16_bf16 v[112:127], v[192:195], v[172:175], v[112:127]
	v_mfma_f32_32x32x16_bf16 v[96:111], v[196:199], v[172:175], v[96:111]
	v_mfma_f32_32x32x16_bf16 v[112:127], v[200:203], v[168:171], v[112:127]
	v_mfma_f32_32x32x16_bf16 v[96:111], v[204:207], v[168:171], v[96:111]
	s_waitcnt lgkmcnt(6)
	v_mfma_f32_32x32x16_bf16 v[48:63], v[132:135], v[144:147], v[48:63]
	ds_read_b64_tr_b16 v[144:145], v252 offset:40960
	ds_read_b64_tr_b16 v[146:147], v252 offset:43008
	v_exp_f32_e32 v64, v64
	v_exp_f32_e32 v65, v65
	s_waitcnt lgkmcnt(6)
	v_mfma_f32_32x32x16_bf16 v[32:47], v[132:135], v[148:151], v[32:47]
	ds_read_b64_tr_b16 v[148:149], v252 offset:41472
	ds_read_b64_tr_b16 v[150:151], v252 offset:43520
	v_exp_f32_e32 v66, v66
	v_exp_f32_e32 v67, v67
	v_add_f32_e32 v182, v64, v182
	v_add_f32_e32 v182, v65, v182
	v_cvt_pk_bf16_f32 v136, v64, v65
	s_waitcnt lgkmcnt(6)
	v_mfma_f32_32x32x16_bf16 v[16:31], v[132:135], v[152:155], v[16:31]
	ds_read_b64_tr_b16 v[152:153], v252 offset:41984
	ds_read_b64_tr_b16 v[154:155], v252 offset:44032
	v_exp_f32_e32 v68, v68
	v_exp_f32_e32 v69, v69
	v_add_f32_e32 v182, v66, v182
	v_add_f32_e32 v182, v67, v182
	v_cvt_pk_bf16_f32 v137, v66, v67
	s_waitcnt lgkmcnt(6)
	v_mfma_f32_32x32x16_bf16 v[0:15], v[132:135], v[156:159], v[0:15]
	ds_read_b64_tr_b16 v[156:157], v252 offset:42496
	ds_read_b64_tr_b16 v[158:159], v252 offset:44544
	v_exp_f32_e32 v70, v70
	v_exp_f32_e32 v71, v71
	v_add_f32_e32 v182, v68, v182
	v_add_f32_e32 v182, v69, v182
	v_cvt_pk_bf16_f32 v138, v68, v69
	v_add_f32_e32 v182, v70, v182
	v_add_f32_e32 v182, v71, v182
	v_cvt_pk_bf16_f32 v139, v70, v71
	v_mfma_f32_32x32x16_bf16 v[112:127], v[208:211], v[164:167], v[112:127]
	v_mfma_f32_32x32x16_bf16 v[96:111], v[212:215], v[164:167], v[96:111]
	v_mfma_f32_32x32x16_bf16 v[112:127], v[216:219], v[160:163], v[112:127]
	v_mfma_f32_32x32x16_bf16 v[96:111], v[220:223], v[160:163], v[96:111]
	s_waitcnt lgkmcnt(6)
	v_mfma_f32_32x32x16_bf16 v[48:63], v[136:139], v[144:147], v[48:63]
	ds_read_b64_tr_b16 v[144:145], v252 offset:45056
	ds_read_b64_tr_b16 v[146:147], v252 offset:47104
	v_exp_f32_e32 v72, v72
	v_exp_f32_e32 v73, v73
	s_waitcnt lgkmcnt(6)
	v_mfma_f32_32x32x16_bf16 v[32:47], v[136:139], v[148:151], v[32:47]
	ds_read_b64_tr_b16 v[148:149], v252 offset:45568
	ds_read_b64_tr_b16 v[150:151], v252 offset:47616
	v_exp_f32_e32 v74, v74
	v_exp_f32_e32 v75, v75
	v_add_f32_e32 v182, v72, v182
	v_add_f32_e32 v182, v73, v182
	v_cvt_pk_bf16_f32 v140, v72, v73
	s_waitcnt lgkmcnt(6)
	v_mfma_f32_32x32x16_bf16 v[16:31], v[136:139], v[152:155], v[16:31]
	ds_read_b64_tr_b16 v[152:153], v252 offset:46080
	ds_read_b64_tr_b16 v[154:155], v252 offset:48128
	v_exp_f32_e32 v76, v76
	v_exp_f32_e32 v77, v77
	v_add_f32_e32 v182, v74, v182
	v_add_f32_e32 v182, v75, v182
	v_cvt_pk_bf16_f32 v141, v74, v75
	s_waitcnt lgkmcnt(6)
	v_mfma_f32_32x32x16_bf16 v[0:15], v[136:139], v[156:159], v[0:15]
	ds_read_b64_tr_b16 v[156:157], v252 offset:46592
	ds_read_b64_tr_b16 v[158:159], v252 offset:48640
	v_exp_f32_e32 v78, v78
	v_exp_f32_e32 v79, v79
	v_add_f32_e32 v182, v76, v182
	v_add_f32_e32 v182, v77, v182
	v_cvt_pk_bf16_f32 v142, v76, v77
	v_add_f32_e32 v182, v78, v182
	v_add_f32_e32 v182, v79, v182
	v_cvt_pk_bf16_f32 v143, v78, v79
	s_nop 1
	s_waitcnt lgkmcnt(6)
	v_mfma_f32_32x32x16_bf16 v[48:63], v[140:143], v[144:147], v[48:63]
	v_exp_f32_e32 v112, v112
	v_exp_f32_e32 v113, v113
	s_waitcnt lgkmcnt(4)
	v_mfma_f32_32x32x16_bf16 v[32:47], v[140:143], v[148:151], v[32:47]
	v_exp_f32_e32 v114, v114
	v_exp_f32_e32 v115, v115
	v_add_f32_e32 v182, v112, v182
	v_add_f32_e32 v182, v113, v182
	v_cvt_pk_bf16_f32 v128, v112, v113
	s_waitcnt lgkmcnt(2)
	v_mfma_f32_32x32x16_bf16 v[16:31], v[140:143], v[152:155], v[16:31]
	v_exp_f32_e32 v116, v116
	v_exp_f32_e32 v117, v117
	v_add_f32_e32 v182, v114, v182
	v_add_f32_e32 v182, v115, v182
	v_cvt_pk_bf16_f32 v129, v114, v115
	s_waitcnt lgkmcnt(0)
	v_mfma_f32_32x32x16_bf16 v[0:15], v[140:143], v[156:159], v[0:15]
	v_exp_f32_e32 v118, v118
	v_exp_f32_e32 v119, v119
	v_add_f32_e32 v182, v116, v182
	v_add_f32_e32 v182, v117, v182
	v_cvt_pk_bf16_f32 v130, v116, v117
	v_add_f32_e32 v182, v118, v182
	v_add_f32_e32 v182, v119, v182
	v_cvt_pk_bf16_f32 v131, v118, v119
	s_nop 1
	s_add_i32 s54, s54, 1
	s_cmp_ge_i32 s54, s62
	s_cbranch_scc1 .Lsym_last3
	s_waitcnt vmcnt(0)
	s_barrier
	ds_read_b128 v[192:195], v178 offset:0
	ds_read_b128 v[196:199], v178 offset:8192
	ds_read_b128 v[200:203], v179 offset:0
	ds_read_b128 v[204:207], v179 offset:8192
	ds_read_b128 v[208:211], v180 offset:0
	ds_read_b128 v[212:215], v180 offset:8192
	ds_read_b128 v[216:219], v181 offset:0
	ds_read_b128 v[220:223], v181 offset:8192
	s_add_i32 s53, s54, 2
	s_cmp_le_i32 s53, s62
	s_cbranch_scc0 .Lsym_nostage_s3
	s_add_i32 m0, s25, 0x4000
	s_add_u32 s60, s56, 0x70000
	s_addc_u32 s61, s57, 0
	global_load_lds_dwordx4 v176, s[56:57]
	s_add_i32 m0, s24, 0x4000
	s_nop 0
	global_load_lds_dwordx4 v188, s[56:57]
	s_add_i32 m0, s25, 0x6000
	s_add_u32 s56, s56, 0xe0000
	s_addc_u32 s57, s57, 0
	global_load_lds_dwordx4 v176, s[60:61]
	s_add_i32 m0, s24, 0x6000
	s_nop 0
	global_load_lds_dwordx4 v188, s[60:61]

; template <int KS> __device__ __forceinline__ void pv_ks(f32x16* o, int vb, bf16x8 pa) {
;     const s16x4 l0 = tr_read<v_rd_off(0, KS, 0)>(vb), h0 = tr_read<v_rd_off(0, KS, 1)>(vb), l1 = tr_read<v_rd_off(1, KS, 0)>(vb), h1 = tr_read<v_rd_off(1, KS, 1)>(vb);
;     const s16x4 l2 = tr_read<v_rd_off(2, KS, 0)>(vb), h2 = tr_read<v_rd_off(2, KS, 1)>(vb), l3 = tr_read<v_rd_off(3, KS, 0)>(vb), h3 = tr_read<v_rd_off(3, KS, 1)>(vb);
;     ...
;     asm volatile("s_waitcnt lgkmcnt(6)" ::: "memory"); SBAR();
;     o[0] = __builtin_amdgcn_mfma_f32_32x32x16_bf16(pa, PK(l0, h0), o[0], 0, 0, 0);
;     asm volatile("s_waitcnt lgkmcnt(4)" ::: "memory"); SBAR();
;     o[1] = __builtin_amdgcn_mfma_f32_32x32x16_bf16(pa, PK(l1, h1), o[1], 0, 0, 0);
;     asm volatile("s_waitcnt lgkmcnt(2)" ::: "memory"); SBAR();
;     o[2] = __builtin_amdgcn_mfma_f32_32x32x16_bf16(pa, PK(l2, h2), o[2], 0, 0, 0);
;     asm volatile("s_waitcnt lgkmcnt(0)" ::: "memory"); SBAR();
;     o[3] = __builtin_amdgcn_mfma_f32_32x32x16_bf16(pa, PK(l3, h3), o[3], 0, 0, 0);
;     ...
; }
; __device__ __forceinline__ void pv_d0(f32x16* o, int vb, bf16x8 pa0, bf16x8 pa1, bf16x8 pa2, bf16x8 pa3) {
;     __builtin_amdgcn_s_setprio(1);
;     pv_ks<0>(o, vb, pa0); pv_ks<1>(o, vb, pa1); pv_ks<2>(o, vb, pa2); pv_ks<3>(o, vb, pa3);
;     __builtin_amdgcn_s_setprio(0);
; }
; __device__ __forceinline__ void exp_half(f32x16& p) {
; #pragma unroll
;     for (int r = 0; r < 16; ++r) p[r] = __builtin_amdgcn_exp2f(p[r]);
; }
; __device__ __forceinline__ void pack_p(const f32x16& p0, const f32x16& p1, float& l_reg, bf16x8& pa0, bf16x8& pa1, bf16x8& pa2, bf16x8& pa3) {
;     float ps = 0;
; #pragma unroll
;     for (int r = 0; r < 16; ++r) ps += p0[r];
; #pragma unroll
;     for (int r = 0; r < 16; ++r) ps += p1[r];
;     l_reg += ps;
;     ...
;     PK4(p0, 0, pa0); PK4(p0, 8, pa1); PK4(p1, 0, pa2); PK4(p1, 8, pa3);
;     ...
; }
; template <int ND0> __device__ __forceinline__ void qkt(f32x16& p0, f32x16& p1, const char* Ks, const bf16x8* qr, int r32, int hi, int colB0) {
; #pragma unroll
;     for (int d0 = 0; d0 < ND0; ++d0) { const int cb = colB0 + (d0 * 16 + hi * 8) * 2;
;         const bf16x8 b0 = *reinterpret_cast<const bf16x8*>(Ks + KSWZ(r32, cb));
;         const bf16x8 b1 = *reinterpret_cast<const bf16x8*>(Ks + KSWZ(32 + r32, cb));
;         p0 = __builtin_amdgcn_mfma_f32_32x32x16_bf16(b0, qr[d0], p0, 0, 0, 0);
.Lsym_biasdone_s3:
	s_add_i32 s55, s55, 64
	v_add_f32_e32 v183, 0xc2800000, v183
	ds_read_b64_tr_b16 v[144:145], v252 offset:49152
	ds_read_b64_tr_b16 v[146:147], v252 offset:51200
	ds_read_b64_tr_b16 v[148:149], v252 offset:49664
	ds_read_b64_tr_b16 v[150:151], v252 offset:51712
	ds_read_b64_tr_b16 v[152:153], v252 offset:50176
	ds_read_b64_tr_b16 v[154:155], v252 offset:52224
	ds_read_b64_tr_b16 v[156:157], v252 offset:50688
	ds_read_b64_tr_b16 v[158:159], v252 offset:52736
	s_waitcnt lgkmcnt(6)
	v_mfma_f32_32x32x16_bf16 v[48:63], v[128:131], v[144:147], v[48:63]
	ds_read_b64_tr_b16 v[144:145], v252 offset:53248
	ds_read_b64_tr_b16 v[146:147], v252 offset:55296
	v_exp_f32_e32 v120, v120
	v_exp_f32_e32 v121, v121
	s_waitcnt lgkmcnt(6)
	v_mfma_f32_32x32x16_bf16 v[32:47], v[128:131], v[148:151], v[32:47]
	ds_read_b64_tr_b16 v[148:149], v252 offset:53760
	ds_read_b64_tr_b16 v[150:151], v252 offset:55808
	v_exp_f32_e32 v122, v122
	v_exp_f32_e32 v123, v123
	v_add_f32_e32 v182, v120, v182
	v_add_f32_e32 v182, v121, v182
	v_cvt_pk_bf16_f32 v132, v120, v121
	s_waitcnt lgkmcnt(6)
	v_mfma_f32_32x32x16_bf16 v[16:31], v[128:131], v[152:155], v[16:31]
	ds_read_b64_tr_b16 v[152:153], v252 offset:54272
	ds_read_b64_tr_b16 v[154:155], v252 offset:56320
	v_exp_f32_e32 v124, v124
	v_exp_f32_e32 v125, v125
	v_add_f32_e32 v182, v122, v182
	v_add_f32_e32 v182, v123, v182
	v_cvt_pk_bf16_f32 v133, v122, v123
	s_waitcnt lgkmcnt(6)
	v_mfma_f32_32x32x16_bf16 v[0:15], v[128:131], v[156:159], v[0:15]
	ds_read_b64_tr_b16 v[156:157], v252 offset:54784
	ds_read_b64_tr_b16 v[158:159], v252 offset:56832
	v_exp_f32_e32 v126, v126
	v_exp_f32_e32 v127, v127
	v_add_f32_e32 v182, v124, v182
	v_add_f32_e32 v182, v125, v182
	v_cvt_pk_bf16_f32 v134, v124, v125
	v_add_f32_e32 v182, v126, v182
	v_add_f32_e32 v182, v127, v182
	v_cvt_pk_bf16_f32 v135, v126, v127
	v_mfma_f32_32x32x16_bf16 v[80:95], v[192:195], v[172:175], v[80:95]
	v_mfma_f32_32x32x16_bf16 v[64:79], v[196:199], v[172:175], v[64:79]
	v_mfma_f32_32x32x16_bf16 v[80:95], v[200:203], v[168:171], v[80:95]
	v_mfma_f32_32x32x16_bf16 v[64:79], v[204:207], v[168:171], v[64:79]
	s_waitcnt lgkmcnt(6)
	v_mfma_f32_32x32x16_bf16 v[48:63], v[132:135], v[144:147], v[48:63]
	ds_read_b64_tr_b16 v[144:145], v252 offset:57344
	ds_read_b64_tr_b16 v[146:147], v252 offset:59392
	v_exp_f32_e32 v96, v96
	v_exp_f32_e32 v97, v97
	s_waitcnt lgkmcnt(6)
	v_mfma_f32_32x32x16_bf16 v[32:47], v[132:135], v[148:151], v[32:47]
	ds_read_b64_tr_b16 v[148:149], v252 offset:57856
	ds_read_b64_tr_b16 v[150:151], v252 offset:59904
	v_exp_f32_e32 v98, v98
	v_exp_f32_e32 v99, v99
	v_add_f32_e32 v182, v96, v182
	v_add_f32_e32 v182, v97, v182
	v_cvt_pk_bf16_f32 v136, v96, v97
	s_waitcnt lgkmcnt(6)
	v_mfma_f32_32x32x16_bf16 v[16:31], v[132:135], v[152:155], v[16:31]
	ds_read_b64_tr_b16 v[152:153], v252 offset:58368
	ds_read_b64_tr_b16 v[154:155], v252 offset:60416
	v_exp_f32_e32 v100, v100
	v_exp_f32_e32 v101, v101
	v_add_f32_e32 v182, v98, v182
	v_add_f32_e32 v182, v99, v182
	v_cvt_pk_bf16_f32 v137, v98, v99
	s_waitcnt lgkmcnt(6)
	v_mfma_f32_32x32x16_bf16 v[0:15], v[132:135], v[156:159], v[0:15]
	ds_read_b64_tr_b16 v[156:157], v252 offset:58880
	ds_read_b64_tr_b16 v[158:159], v252 offset:60928
	v_exp_f32_e32 v102, v102
	v_exp_f32_e32 v103, v103
	v_add_f32_e32 v182, v100, v182
	v_add_f32_e32 v182, v101, v182
	v_cvt_pk_bf16_f32 v138, v100, v101
	v_add_f32_e32 v182, v102, v182
	v_add_f32_e32 v182, v103, v182
	v_cvt_pk_bf16_f32 v139, v102, v103
	v_mfma_f32_32x32x16_bf16 v[80:95], v[208:211], v[164:167], v[80:95]
	v_mfma_f32_32x32x16_bf16 v[64:79], v[212:215], v[164:167], v[64:79]
	v_mfma_f32_32x32x16_bf16 v[80:95], v[216:219], v[160:163], v[80:95]
	v_mfma_f32_32x32x16_bf16 v[64:79], v[220:223], v[160:163], v[64:79]
	s_waitcnt lgkmcnt(6)
	v_mfma_f32_32x32x16_bf16 v[48:63], v[136:139], v[144:147], v[48:63]
	ds_read_b64_tr_b16 v[144:145], v252 offset:61440
	ds_read_b64_tr_b16 v[146:147], v252 offset:63488
	v_exp_f32_e32 v104, v104
	v_exp_f32_e32 v105, v105
	s_waitcnt lgkmcnt(6)
	v_mfma_f32_32x32x16_bf16 v[32:47], v[136:139], v[148:151], v[32:47]
	ds_read_b64_tr_b16 v[148:149], v252 offset:61952
	ds_read_b64_tr_b16 v[150:151], v252 offset:64000
	v_exp_f32_e32 v106, v106
	v_exp_f32_e32 v107, v107
	v_add_f32_e32 v182, v104, v182
	v_add_f32_e32 v182, v105, v182
	v_cvt_pk_bf16_f32 v140, v104, v105
	s_waitcnt lgkmcnt(6)
	v_mfma_f32_32x32x16_bf16 v[16:31], v[136:139], v[152:155], v[16:31]
	ds_read_b64_tr_b16 v[152:153], v252 offset:62464
	ds_read_b64_tr_b16 v[154:155], v252 offset:64512
	v_exp_f32_e32 v108, v108
	v_exp_f32_e32 v109, v109
	v_add_f32_e32 v182, v106, v182
	v_add_f32_e32 v182, v107, v182
	v_cvt_pk_bf16_f32 v141, v106, v107
	s_waitcnt lgkmcnt(6)
	v_mfma_f32_32x32x16_bf16 v[0:15], v[136:139], v[156:159], v[0:15]
	ds_read_b64_tr_b16 v[156:157], v252 offset:62976
	ds_read_b64_tr_b16 v[158:159], v252 offset:65024
	v_exp_f32_e32 v110, v110
	v_exp_f32_e32 v111, v111
	v_add_f32_e32 v182, v108, v182
	v_add_f32_e32 v182, v109, v182
	v_cvt_pk_bf16_f32 v142, v108, v109
	v_add_f32_e32 v182, v110, v182
	v_add_f32_e32 v182, v111, v182
	v_cvt_pk_bf16_f32 v143, v110, v111
	s_nop 1
	s_waitcnt lgkmcnt(6)
	v_mfma_f32_32x32x16_bf16 v[48:63], v[140:143], v[144:147], v[48:63]
	v_exp_f32_e32 v80, v80
	v_exp_f32_e32 v81, v81
	s_waitcnt lgkmcnt(4)
	v_mfma_f32_32x32x16_bf16 v[32:47], v[140:143], v[148:151], v[32:47]
	v_exp_f32_e32 v82, v82
	v_exp_f32_e32 v83, v83
	v_add_f32_e32 v182, v80, v182
	v_add_f32_e32 v182, v81, v182
	v_cvt_pk_bf16_f32 v128, v80, v81
	s_waitcnt lgkmcnt(2)
	v_mfma_f32_32x32x16_bf16 v[16:31], v[140:143], v[152:155], v[16:31]
	v_exp_f32_e32 v84, v84
	v_exp_f32_e32 v85, v85
	v_add_f32_e32 v182, v82, v182
	v_add_f32_e32 v182, v83, v182
	v_cvt_pk_bf16_f32 v129, v82, v83
	s_waitcnt lgkmcnt(0)
	v_mfma_f32_32x32x16_bf16 v[0:15], v[140:143], v[156:159], v[0:15]
	v_exp_f32_e32 v86, v86
	v_exp_f32_e32 v87, v87
	v_add_f32_e32 v182, v84, v182
	v_add_f32_e32 v182, v85, v182
	v_cvt_pk_bf16_f32 v130, v84, v85
	v_add_f32_e32 v182, v86, v182
	v_add_f32_e32 v182, v87, v182
	v_cvt_pk_bf16_f32 v131, v86, v87
	s_nop 1
	s_add_i32 s54, s54, 1
	s_branch .Lsym_loop
